# prompt-scan chunk bodies: batch lgkmcnt(0) waits replaced by a machine-derived counted lgkmcnt ladder (each ds_read waited at its first use)
# speedup vs baseline: 1.0058x; 1.0058x over previous
; DI void scan_chunk(const float* buf, f32x4& S, int w, int rw, int kg, float& ys) {
;   float yp[16];
; #pragma unroll
;   for (int s = 0; s < 16; ++s) {
;     const float* b = buf + s * 64 + kg * 4;
;     f32x4 d = *(const f32x4*)(b), n = *(const f32x4*)(b + 1024), a = *(const f32x4*)(b + 2048), k = *(const f32x4*)(b + 3072),
;           r = *(const f32x4*)(b + 4096);
;     float vv = buf[5120 + s * 16 + w * 4 + rw];
;     float pp = S[0] * n[0];
;     pp = fmaf(S[1], n[1], pp); pp = fmaf(S[2], n[2], pp); pp = fmaf(S[3], n[3], pp);
;     float sa = row_allreduce(pp);
; #pragma unroll
;     for (int e = 0; e < 4; ++e) S[e] = fmaf(sa, a[e], fmaf(S[e], d[e], vv * k[e]));
;     float y = S[0] * r[0];
;     y = fmaf(S[1], r[1], y); y = fmaf(S[2], r[2], y); y = fmaf(S[3], r[3], y);
;     yp[s] = y;
;   }
.LBB0_186:
	ds_read_b128 v[62:65], v51 offset:4096
	v_add_u32_e32 v46, 0x5000, v55
	ds_read_b128 v[66:69], v51 offset:4352
	ds_read2_b32 v[130:131], v46 offset1:16
	s_add_i32 s28, s20, -2
	s_cmp_lt_u32 s28, s39
	s_waitcnt lgkmcnt(2)
	v_mul_f32_e32 v0, v26, v62
	v_fmac_f32_e32 v0, v27, v63
	v_fmac_f32_e32 v0, v28, v64
	v_fmac_f32_e32 v0, v29, v65
	ds_read_b128 v[62:65], v51
	ds_read_b128 v[70:73], v51 offset:256
	ds_read_b128 v[74:77], v51 offset:8192
	ds_read_b128 v[78:81], v51 offset:8448
	ds_read_b128 v[82:85], v51 offset:12288
	ds_read_b128 v[86:89], v51 offset:12544
	ds_read_b128 v[90:93], v51 offset:16384
	ds_read_b128 v[94:97], v51 offset:16640
	ds_read2_b32 v[158:159], v46 offset0:32 offset1:48
	ds_read_b128 v[98:101], v51 offset:512
	ds_read_b128 v[102:105], v51 offset:768
	ds_read_b128 v[106:109], v51 offset:4608
	ds_read_b128 v[110:113], v51 offset:4864
	ds_read_b128 v[114:117], v51 offset:8704
	ds_read_b128 v[118:121], v51 offset:8960
	ds_read_b128 v[122:125], v51 offset:12800
	ds_read_b128 v[126:129], v51 offset:13056
	ds_read_b128 v[138:141], v51 offset:16896
	ds_read_b128 v[142:145], v51 offset:17152
	ds_read_b128 v[146:149], v51 offset:1024
	ds_read_b128 v[150:153], v51 offset:5120
	ds_read_b128 v[154:157], v51 offset:13312
	ds_read2_b32 v[44:45], v46 offset0:64 offset1:80
	v_add_f32_dpp v0, v0, v0 row_ror:8 row_mask:0xf bank_mask:0xf bound_ctrl:1
	s_waitcnt lgkmcnt(15)
	v_pk_mul_f32 v[82:83], v[82:83], v[130:131] op_sel_hi:[1,0]
	v_pk_mul_f32 v[84:85], v[84:85], v[130:131] op_sel_hi:[1,0]
	v_add_f32_dpp v0, v0, v0 row_ror:4 row_mask:0xf bank_mask:0xf bound_ctrl:1
	v_pk_fma_f32 v[26:27], v[26:27], v[62:63], v[82:83]
	v_pk_fma_f32 v[28:29], v[28:29], v[64:65], v[84:85]
	v_add_f32_dpp v0, v0, v0 row_ror:2 row_mask:0xf bank_mask:0xf bound_ctrl:1
	s_waitcnt lgkmcnt(14)
	v_mov_b32_e32 v84, v159
	s_cselect_b64 s[8:9], -1, 0
	v_add_f32_dpp v0, v0, v0 row_ror:1 row_mask:0xf bank_mask:0xf bound_ctrl:1
	v_pk_fma_f32 v[26:27], v[0:1], v[74:75], v[26:27] op_sel_hi:[0,1,1]
	v_mul_f32_e32 v47, v66, v26
	v_pk_fma_f32 v[64:65], v[0:1], v[76:77], v[28:29] op_sel_hi:[0,1,1]
	v_fmac_f32_e32 v47, v27, v67
	v_fmac_f32_e32 v47, v64, v68
	v_fmac_f32_e32 v47, v65, v69
	v_mov_b32_e32 v28, v131
	v_mul_f32_e32 v0, v90, v26
	v_add_f32_dpp v47, v47, v47 row_ror:8 row_mask:0xf bank_mask:0xf bound_ctrl:1
	v_pk_mul_f32 v[76:77], v[88:89], v[28:29] op_sel_hi:[1,0]
	v_fmac_f32_e32 v0, v27, v91
	v_add_f32_dpp v47, v47, v47 row_ror:4 row_mask:0xf bank_mask:0xf bound_ctrl:1
	v_pk_mul_f32 v[28:29], v[86:87], v[28:29] op_sel_hi:[1,0]
	v_pk_fma_f32 v[72:73], v[64:65], v[72:73], v[76:77]
	v_add_f32_dpp v47, v47, v47 row_ror:2 row_mask:0xf bank_mask:0xf bound_ctrl:1
	v_pk_fma_f32 v[62:63], v[26:27], v[70:71], v[28:29]
	v_fmac_f32_e32 v0, v64, v92
	v_add_f32_dpp v64, v47, v47 row_ror:1 row_mask:0xf bank_mask:0xf bound_ctrl:1
	v_pk_fma_f32 v[62:63], v[64:65], v[78:79], v[62:63] op_sel_hi:[0,1,1]
	s_waitcnt lgkmcnt(11)
	v_mul_f32_e32 v68, v106, v62
	v_fmac_f32_e32 v0, v65, v93
	v_pk_fma_f32 v[64:65], v[64:65], v[80:81], v[72:73] op_sel_hi:[0,1,1]
	v_fmac_f32_e32 v68, v63, v107
	v_fmac_f32_e32 v68, v64, v108
	v_fmac_f32_e32 v68, v65, v109
	s_waitcnt lgkmcnt(7)
	v_pk_mul_f32 v[66:67], v[122:123], v[158:159] op_sel_hi:[1,0]
	v_mul_f32_e32 v47, v94, v62
	v_add_f32_dpp v68, v68, v68 row_ror:8 row_mask:0xf bank_mask:0xf bound_ctrl:1
	v_pk_mul_f32 v[76:77], v[124:125], v[158:159] op_sel_hi:[1,0]
	v_fmac_f32_e32 v47, v63, v95
	v_add_f32_dpp v68, v68, v68 row_ror:4 row_mask:0xf bank_mask:0xf bound_ctrl:1
	v_pk_fma_f32 v[62:63], v[62:63], v[98:99], v[66:67]
	v_fmac_f32_e32 v47, v64, v96
	v_add_f32_dpp v68, v68, v68 row_ror:2 row_mask:0xf bank_mask:0xf bound_ctrl:1
	v_fmac_f32_e32 v47, v65, v97
	s_waitcnt lgkmcnt(6)
	v_pk_mul_f32 v[70:71], v[126:127], v[84:85] op_sel_hi:[1,0]
	v_add_f32_dpp v68, v68, v68 row_ror:1 row_mask:0xf bank_mask:0xf bound_ctrl:1
	v_pk_fma_f32 v[66:67], v[68:69], v[114:115], v[62:63] op_sel_hi:[0,1,1]
	v_pk_fma_f32 v[62:63], v[64:65], v[100:101], v[76:77]
	v_pk_mul_f32 v[88:89], v[128:129], v[84:85] op_sel_hi:[1,0]
	v_pk_fma_f32 v[64:65], v[68:69], v[116:117], v[62:63] op_sel_hi:[0,1,1]
	v_mul_f32_e32 v63, v110, v66
	v_fmac_f32_e32 v63, v67, v111
	v_fmac_f32_e32 v63, v64, v112
	v_fmac_f32_e32 v63, v65, v113
	s_waitcnt lgkmcnt(5)
	v_mul_f32_e32 v62, v138, v66
	v_fmac_f32_e32 v62, v67, v139
	v_add_f32_dpp v63, v63, v63 row_ror:8 row_mask:0xf bank_mask:0xf bound_ctrl:1
	v_fmac_f32_e32 v62, v64, v140
	v_pk_fma_f32 v[66:67], v[66:67], v[102:103], v[70:71]
	v_add_f32_dpp v63, v63, v63 row_ror:4 row_mask:0xf bank_mask:0xf bound_ctrl:1
	v_fmac_f32_e32 v62, v65, v141
	v_pk_fma_f32 v[64:65], v[64:65], v[104:105], v[88:89]
	v_add_f32_dpp v63, v63, v63 row_ror:2 row_mask:0xf bank_mask:0xf bound_ctrl:1
	s_waitcnt lgkmcnt(0)
; DI void scan_chunk(const float* buf, f32x4& S, int w, int rw, int kg, float& ys) {
;   float yp[16];
; #pragma unroll
;   for (int s = 0; s < 16; ++s) {
;     const float* b = buf + s * 64 + kg * 4;
;     f32x4 d = *(const f32x4*)(b), n = *(const f32x4*)(b + 1024), a = *(const f32x4*)(b + 2048), k = *(const f32x4*)(b + 3072),
;           r = *(const f32x4*)(b + 4096);
;     float vv = buf[5120 + s * 16 + w * 4 + rw];
;     float pp = S[0] * n[0];
;     pp = fmaf(S[1], n[1], pp); pp = fmaf(S[2], n[2], pp); pp = fmaf(S[3], n[3], pp);
;     float sa = row_allreduce(pp);
; #pragma unroll
;     for (int e = 0; e < 4; ++e) S[e] = fmaf(sa, a[e], fmaf(S[e], d[e], vv * k[e]));
;     float y = S[0] * r[0];
;     y = fmaf(S[1], r[1], y); y = fmaf(S[2], r[2], y); y = fmaf(S[3], r[3], y);
;     yp[s] = y;
;   }
	v_pk_mul_f32 v[74:75], v[154:155], v[44:45] op_sel_hi:[1,0]
	ds_read_b128 v[26:29], v51 offset:13568
	v_add_f32_dpp v68, v63, v63 row_ror:1 row_mask:0xf bank_mask:0xf bound_ctrl:1
	v_pk_fma_f32 v[72:73], v[68:69], v[118:119], v[66:67] op_sel_hi:[0,1,1]
	v_pk_fma_f32 v[76:77], v[68:69], v[120:121], v[64:65] op_sel_hi:[0,1,1]
	v_mul_f32_e32 v68, v150, v72
	v_fmac_f32_e32 v68, v73, v151
	v_fmac_f32_e32 v68, v76, v152
	v_fmac_f32_e32 v68, v77, v153
	v_mul_f32_e32 v63, v142, v72
	ds_read_b128 v[64:67], v51 offset:5376
	v_add_f32_dpp v68, v68, v68 row_ror:8 row_mask:0xf bank_mask:0xf bound_ctrl:1
	v_fmac_f32_e32 v63, v73, v143
	v_fmac_f32_e32 v63, v76, v144
	v_add_f32_dpp v68, v68, v68 row_ror:4 row_mask:0xf bank_mask:0xf bound_ctrl:1
	v_pk_fma_f32 v[188:189], v[72:73], v[146:147], v[74:75]
	v_pk_mul_f32 v[72:73], v[156:157], v[44:45] op_sel_hi:[1,0]
	v_add_f32_dpp v68, v68, v68 row_ror:2 row_mask:0xf bank_mask:0xf bound_ctrl:1
	v_fmac_f32_e32 v63, v77, v145
	v_pk_fma_f32 v[190:191], v[76:77], v[148:149], v[72:73]
	v_add_f32_dpp v186, v68, v68 row_ror:1 row_mask:0xf bank_mask:0xf bound_ctrl:1
	ds_read_b128 v[68:71], v51 offset:1280
	ds_read_b128 v[72:75], v51 offset:9216
	ds_read_b128 v[76:79], v51 offset:9472
	ds_read_b128 v[80:83], v51 offset:17408
	ds_read_b128 v[84:87], v51 offset:17664
	ds_read2_b32 v[192:193], v46 offset0:96 offset1:112
	ds_read_b128 v[88:91], v51 offset:1536
	ds_read_b128 v[92:95], v51 offset:1792
	ds_read_b128 v[96:99], v51 offset:5632
	ds_read_b128 v[100:103], v51 offset:5888
	ds_read_b128 v[104:107], v51 offset:9728
	ds_read_b128 v[108:111], v51 offset:9984
	ds_read_b128 v[112:115], v51 offset:13824
	ds_read_b128 v[116:119], v51 offset:14080
	ds_read_b128 v[120:123], v51 offset:17920
	ds_read_b128 v[124:127], v51 offset:18176
	ds_read2_b32 v[194:195], v46 offset0:128 offset1:144
	ds_read_b128 v[128:131], v51 offset:2048
	ds_read_b128 v[138:141], v51 offset:2304
	ds_read_b128 v[142:145], v51 offset:6144
	ds_read_b128 v[146:149], v51 offset:6400
	ds_read_b128 v[150:153], v51 offset:10240
	ds_read_b128 v[154:157], v51 offset:10496
	ds_read_b128 v[158:161], v51 offset:14336
	ds_read_b128 v[162:165], v51 offset:14592
	ds_read_b128 v[172:175], v51 offset:18432
	ds_read_b128 v[182:185], v51 offset:18688
	s_waitcnt lgkmcnt(15)
	v_pk_fma_f32 v[72:73], v[186:187], v[72:73], v[188:189] op_sel_hi:[0,1,1]
	v_mul_f32_e32 v181, v64, v72
	v_fmac_f32_e32 v181, v73, v65
	v_pk_fma_f32 v[74:75], v[186:187], v[74:75], v[190:191] op_sel_hi:[0,1,1]
	v_fmac_f32_e32 v181, v74, v66
	v_fmac_f32_e32 v181, v75, v67
	v_mov_b32_e32 v44, v45
	v_pk_mul_f32 v[26:27], v[26:27], v[44:45] op_sel_hi:[1,0]
	v_add_f32_dpp v66, v181, v181 row_ror:8 row_mask:0xf bank_mask:0xf bound_ctrl:1
	v_pk_fma_f32 v[26:27], v[72:73], v[68:69], v[26:27]
	v_pk_mul_f32 v[28:29], v[28:29], v[44:45] op_sel_hi:[1,0]
	v_add_f32_dpp v66, v66, v66 row_ror:4 row_mask:0xf bank_mask:0xf bound_ctrl:1
	v_pk_fma_f32 v[28:29], v[74:75], v[70:71], v[28:29]
	s_waitcnt lgkmcnt(14)
	v_pk_mul_f32 v[64:65], v[112:113], v[192:193] op_sel_hi:[1,0]
	v_add_f32_dpp v66, v66, v66 row_ror:2 row_mask:0xf bank_mask:0xf bound_ctrl:1
	v_pk_mul_f32 v[44:45], v[114:115], v[192:193] op_sel_hi:[1,0]
	v_mul_f32_e32 v135, v80, v72
	v_add_f32_dpp v66, v66, v66 row_ror:1 row_mask:0xf bank_mask:0xf bound_ctrl:1
	v_pk_fma_f32 v[26:27], v[66:67], v[76:77], v[26:27] op_sel_hi:[0,1,1]
	v_pk_fma_f32 v[28:29], v[66:67], v[78:79], v[28:29] op_sel_hi:[0,1,1]
	v_mul_f32_e32 v66, v96, v26
	v_fmac_f32_e32 v66, v27, v97
	v_fmac_f32_e32 v66, v28, v98
	v_fmac_f32_e32 v66, v29, v99
	v_mul_f32_e32 v181, v84, v26
	v_fmac_f32_e32 v181, v27, v85
	v_add_f32_dpp v66, v66, v66 row_ror:8 row_mask:0xf bank_mask:0xf bound_ctrl:1
	v_pk_fma_f32 v[26:27], v[26:27], v[88:89], v[64:65]
	v_fmac_f32_e32 v181, v28, v86
	v_add_f32_dpp v66, v66, v66 row_ror:4 row_mask:0xf bank_mask:0xf bound_ctrl:1
	v_fmac_f32_e32 v181, v29, v87
	v_pk_fma_f32 v[28:29], v[28:29], v[90:91], v[44:45]
	v_add_f32_dpp v66, v66, v66 row_ror:2 row_mask:0xf bank_mask:0xf bound_ctrl:1
	v_fmac_f32_e32 v135, v73, v81
	v_mov_b32_e32 v68, v193
	v_add_f32_dpp v66, v66, v66 row_ror:1 row_mask:0xf bank_mask:0xf bound_ctrl:1
	v_pk_fma_f32 v[26:27], v[66:67], v[104:105], v[26:27] op_sel_hi:[0,1,1]
	v_mul_f32_e32 v44, v100, v26
	v_pk_fma_f32 v[28:29], v[66:67], v[106:107], v[28:29] op_sel_hi:[0,1,1]
	v_fmac_f32_e32 v44, v27, v101
	v_fmac_f32_e32 v44, v28, v102
	v_fmac_f32_e32 v44, v29, v103
	s_waitcnt lgkmcnt(3)
	v_pk_mul_f32 v[80:81], v[158:159], v[194:195] op_sel_hi:[1,0]
	v_mov_b32_e32 v112, v195
	v_add_f32_dpp v44, v44, v44 row_ror:8 row_mask:0xf bank_mask:0xf bound_ctrl:1
	v_pk_mul_f32 v[70:71], v[160:161], v[194:195] op_sel_hi:[1,0]
	v_mul_f32_e32 v195, v120, v26
	v_add_f32_dpp v44, v44, v44 row_ror:4 row_mask:0xf bank_mask:0xf bound_ctrl:1
	v_pk_mul_f32 v[72:73], v[116:117], v[68:69] op_sel_hi:[1,0]
	v_fmac_f32_e32 v195, v27, v121
	v_add_f32_dpp v44, v44, v44 row_ror:2 row_mask:0xf bank_mask:0xf bound_ctrl:1
	v_pk_mul_f32 v[68:69], v[118:119], v[68:69] op_sel_hi:[1,0]
	v_fmac_f32_e32 v195, v28, v122
	v_add_f32_dpp v44, v44, v44 row_ror:1 row_mask:0xf bank_mask:0xf bound_ctrl:1
	v_pk_fma_f32 v[26:27], v[26:27], v[92:93], v[72:73]
	v_fmac_f32_e32 v195, v29, v123
	v_pk_fma_f32 v[26:27], v[44:45], v[108:109], v[26:27] op_sel_hi:[0,1,1]
	v_pk_fma_f32 v[28:29], v[28:29], v[94:95], v[68:69]
	v_mul_f32_e32 v204, v124, v26
	v_pk_fma_f32 v[28:29], v[44:45], v[110:111], v[28:29] op_sel_hi:[0,1,1]
	v_mul_f32_e32 v44, v142, v26
	v_fmac_f32_e32 v44, v27, v143
	v_fmac_f32_e32 v44, v28, v144
	v_fmac_f32_e32 v44, v29, v145
	v_fmac_f32_e32 v204, v27, v125
	v_fmac_f32_e32 v204, v28, v126
	v_add_f32_dpp v44, v44, v44 row_ror:8 row_mask:0xf bank_mask:0xf bound_ctrl:1
	v_pk_fma_f32 v[26:27], v[26:27], v[128:129], v[80:81]
	v_fmac_f32_e32 v204, v29, v127
	v_add_f32_dpp v44, v44, v44 row_ror:4 row_mask:0xf bank_mask:0xf bound_ctrl:1
	v_pk_fma_f32 v[28:29], v[28:29], v[130:131], v[70:71]
	s_waitcnt lgkmcnt(2)
; DI void scan_chunk(const float* buf, f32x4& S, int w, int rw, int kg, float& ys) {
;   float yp[16];
; #pragma unroll
;   for (int s = 0; s < 16; ++s) {
;     const float* b = buf + s * 64 + kg * 4;
;     f32x4 d = *(const f32x4*)(b), n = *(const f32x4*)(b + 1024), a = *(const f32x4*)(b + 2048), k = *(const f32x4*)(b + 3072),
;           r = *(const f32x4*)(b + 4096);
;     float vv = buf[5120 + s * 16 + w * 4 + rw];
;     float pp = S[0] * n[0];
;     pp = fmaf(S[1], n[1], pp); pp = fmaf(S[2], n[2], pp); pp = fmaf(S[3], n[3], pp);
;     float sa = row_allreduce(pp);
; #pragma unroll
;     for (int e = 0; e < 4; ++e) S[e] = fmaf(sa, a[e], fmaf(S[e], d[e], vv * k[e]));
;     float y = S[0] * r[0];
;     y = fmaf(S[1], r[1], y); y = fmaf(S[2], r[2], y); y = fmaf(S[3], r[3], y);
;     yp[s] = y;
;   }
	v_pk_mul_f32 v[116:117], v[162:163], v[112:113] op_sel_hi:[1,0]
	v_add_f32_dpp v44, v44, v44 row_ror:2 row_mask:0xf bank_mask:0xf bound_ctrl:1
	v_fmac_f32_e32 v135, v74, v82
	v_fmac_f32_e32 v135, v75, v83
	v_add_f32_dpp v44, v44, v44 row_ror:1 row_mask:0xf bank_mask:0xf bound_ctrl:1
	v_pk_fma_f32 v[26:27], v[44:45], v[150:151], v[26:27] op_sel_hi:[0,1,1]
	v_pk_fma_f32 v[28:29], v[44:45], v[152:153], v[28:29] op_sel_hi:[0,1,1]
	v_mul_f32_e32 v44, v146, v26
	v_fmac_f32_e32 v44, v27, v147
	v_fmac_f32_e32 v44, v28, v148
	v_fmac_f32_e32 v44, v29, v149
	s_waitcnt lgkmcnt(1)
	v_mul_f32_e32 v206, v172, v26
	v_fmac_f32_e32 v206, v27, v173
	v_add_f32_dpp v44, v44, v44 row_ror:8 row_mask:0xf bank_mask:0xf bound_ctrl:1
	v_pk_fma_f32 v[26:27], v[26:27], v[138:139], v[116:117]
	v_fmac_f32_e32 v206, v28, v174
	v_add_f32_dpp v44, v44, v44 row_ror:4 row_mask:0xf bank_mask:0xf bound_ctrl:1
	v_fmac_f32_e32 v206, v29, v175
	s_cmp_ge_u32 s28, s39
	v_add_f32_dpp v44, v44, v44 row_ror:2 row_mask:0xf bank_mask:0xf bound_ctrl:1
	s_nop 1
	v_add_f32_dpp v44, v44, v44 row_ror:1 row_mask:0xf bank_mask:0xf bound_ctrl:1
	v_pk_fma_f32 v[190:191], v[44:45], v[154:155], v[26:27] op_sel_hi:[0,1,1]
	v_pk_mul_f32 v[26:27], v[164:165], v[112:113] op_sel_hi:[1,0]
	s_waitcnt lgkmcnt(0)
	v_mul_f32_e32 v207, v182, v190
	v_pk_fma_f32 v[26:27], v[28:29], v[140:141], v[26:27]
	v_fmac_f32_e32 v207, v191, v183
	v_pk_fma_f32 v[44:45], v[44:45], v[156:157], v[26:27] op_sel_hi:[0,1,1]
	ds_read_b128 v[26:29], v51 offset:6656
	ds_read_b128 v[64:67], v51 offset:14848
	ds_read2_b32 v[192:193], v46 offset0:160 offset1:176
	ds_read_b128 v[68:71], v51 offset:6912
	v_fmac_f32_e32 v207, v44, v184
	v_fmac_f32_e32 v207, v45, v185
	s_waitcnt lgkmcnt(3)
	v_mul_f32_e32 v26, v26, v190
	v_fmac_f32_e32 v26, v191, v27
	v_fmac_f32_e32 v26, v44, v28
	v_fmac_f32_e32 v26, v45, v29
	s_waitcnt lgkmcnt(1)
	v_pk_mul_f32 v[196:197], v[64:65], v[192:193] op_sel_hi:[1,0]
	v_pk_mul_f32 v[198:199], v[66:67], v[192:193] op_sel_hi:[1,0]
	v_add_f32_dpp v26, v26, v26 row_ror:8 row_mask:0xf bank_mask:0xf bound_ctrl:1
	s_nop 1
	v_add_f32_dpp v26, v26, v26 row_ror:4 row_mask:0xf bank_mask:0xf bound_ctrl:1
	s_nop 1
	v_add_f32_dpp v26, v26, v26 row_ror:2 row_mask:0xf bank_mask:0xf bound_ctrl:1
	s_nop 1
	v_add_f32_dpp v194, v26, v26 row_ror:1 row_mask:0xf bank_mask:0xf bound_ctrl:1
	ds_read_b128 v[26:29], v51 offset:15104
	ds_read_b128 v[64:67], v51 offset:2560
	ds_read_b128 v[72:75], v51 offset:2816
	ds_read_b128 v[76:79], v51 offset:10752
	ds_read_b128 v[80:83], v51 offset:11008
	ds_read_b128 v[84:87], v51 offset:18944
	ds_read_b128 v[88:91], v51 offset:19200
	ds_read2_b32 v[200:201], v46 offset0:192 offset1:208
	ds_read_b128 v[92:95], v51 offset:3072
	ds_read_b128 v[96:99], v51 offset:3328
	ds_read_b128 v[100:103], v51 offset:7168
	ds_read_b128 v[104:107], v51 offset:7424
	ds_read_b128 v[108:111], v51 offset:11264
	ds_read_b128 v[112:115], v51 offset:11520
	ds_read_b128 v[116:119], v51 offset:15360
	ds_read_b128 v[120:123], v51 offset:15616
	ds_read_b128 v[124:127], v51 offset:19456
	ds_read_b128 v[128:131], v51 offset:19712
	ds_read2_b32 v[202:203], v46 offset0:224 offset1:240
	ds_read_b128 v[138:141], v51 offset:3584
	ds_read_b128 v[142:145], v51 offset:3840
	ds_read_b128 v[146:149], v51 offset:7680
	ds_read_b128 v[150:153], v51 offset:7936
	ds_read_b128 v[154:157], v51 offset:11776
	ds_read_b128 v[158:161], v51 offset:12032
	ds_read_b128 v[162:165], v51 offset:15872
	ds_read_b128 v[172:175], v51 offset:16128
	ds_read_b128 v[182:185], v51 offset:19968
	ds_read_b128 v[186:189], v51 offset:20224
	s_waitcnt lgkmcnt(15)
	v_pk_fma_f32 v[64:65], v[190:191], v[64:65], v[196:197]
	v_pk_fma_f32 v[44:45], v[44:45], v[66:67], v[198:199]
	s_waitcnt lgkmcnt(15)
	v_pk_fma_f32 v[64:65], v[194:195], v[76:77], v[64:65] op_sel_hi:[0,1,1]
	v_mul_f32_e32 v77, v68, v64
	v_pk_fma_f32 v[44:45], v[194:195], v[78:79], v[44:45] op_sel_hi:[0,1,1]
	v_fmac_f32_e32 v77, v65, v69
	v_mov_b32_e32 v46, v193
	s_waitcnt lgkmcnt(15)
	v_mul_f32_e32 v76, v84, v64
	v_fmac_f32_e32 v77, v44, v70
	v_pk_mul_f32 v[28:29], v[28:29], v[46:47] op_sel_hi:[1,0]
	v_fmac_f32_e32 v76, v65, v85
	v_fmac_f32_e32 v77, v45, v71
	v_pk_fma_f32 v[28:29], v[44:45], v[74:75], v[28:29]
	v_fmac_f32_e32 v76, v44, v86
	v_add_f32_dpp v44, v77, v77 row_ror:8 row_mask:0xf bank_mask:0xf bound_ctrl:1
	v_pk_mul_f32 v[26:27], v[26:27], v[46:47] op_sel_hi:[1,0]
	v_fmac_f32_e32 v76, v45, v87
	v_add_f32_dpp v44, v44, v44 row_ror:4 row_mask:0xf bank_mask:0xf bound_ctrl:1
	v_pk_fma_f32 v[26:27], v[64:65], v[72:73], v[26:27]
	s_waitcnt lgkmcnt(14)
	v_pk_mul_f32 v[64:65], v[116:117], v[200:201] op_sel_hi:[1,0]
	v_add_f32_dpp v44, v44, v44 row_ror:2 row_mask:0xf bank_mask:0xf bound_ctrl:1
	v_pk_mul_f32 v[66:67], v[118:119], v[200:201] op_sel_hi:[1,0]
	v_mov_b32_e32 v74, v201
	v_add_f32_dpp v44, v44, v44 row_ror:1 row_mask:0xf bank_mask:0xf bound_ctrl:1
	v_pk_fma_f32 v[26:27], v[44:45], v[80:81], v[26:27] op_sel_hi:[0,1,1]
	v_pk_fma_f32 v[28:29], v[44:45], v[82:83], v[28:29] op_sel_hi:[0,1,1]
	v_mul_f32_e32 v44, v100, v26
	v_fmac_f32_e32 v44, v27, v101
	v_fmac_f32_e32 v44, v28, v102
	v_fmac_f32_e32 v44, v29, v103
	v_mul_f32_e32 v45, v88, v26
	v_fmac_f32_e32 v45, v27, v89
	v_add_f32_dpp v44, v44, v44 row_ror:8 row_mask:0xf bank_mask:0xf bound_ctrl:1
	v_fmac_f32_e32 v45, v28, v90
	v_fmac_f32_e32 v45, v29, v91
	v_add_f32_dpp v44, v44, v44 row_ror:4 row_mask:0xf bank_mask:0xf bound_ctrl:1
	v_pk_fma_f32 v[26:27], v[26:27], v[92:93], v[64:65]
	v_pk_fma_f32 v[28:29], v[28:29], v[94:95], v[66:67]
	v_add_f32_dpp v44, v44, v44 row_ror:2 row_mask:0xf bank_mask:0xf bound_ctrl:1
	s_waitcnt lgkmcnt(13)
; template <int CTRL> DI float dpp_get(float x) { return __int_as_float(__builtin_amdgcn_update_dpp(0, __float_as_int(x), CTRL, 0xf, 0xf, false)); }
; DI void scan_chunk(const float* buf, f32x4& S, int w, int rw, int kg, float& ys) {
;   float yp[16];
; #pragma unroll
;   for (int s = 0; s < 16; ++s) {
;     const float* b = buf + s * 64 + kg * 4;
;     f32x4 d = *(const f32x4*)(b), n = *(const f32x4*)(b + 1024), a = *(const f32x4*)(b + 2048), k = *(const f32x4*)(b + 3072),
;           r = *(const f32x4*)(b + 4096);
;     float vv = buf[5120 + s * 16 + w * 4 + rw];
;     float pp = S[0] * n[0];
;     pp = fmaf(S[1], n[1], pp); pp = fmaf(S[2], n[2], pp); pp = fmaf(S[3], n[3], pp);
;     float sa = row_allreduce(pp);
; #pragma unroll
;     for (int e = 0; e < 4; ++e) S[e] = fmaf(sa, a[e], fmaf(S[e], d[e], vv * k[e]));
;     float y = S[0] * r[0];
;     y = fmaf(S[1], r[1], y); y = fmaf(S[2], r[2], y); y = fmaf(S[3], r[3], y);
;     yp[s] = y;
;   }
;   const bool b3 = (kg & 8) != 0, b2 = (kg & 4) != 0, b1 = (kg & 2) != 0, b0 = (kg & 1) != 0;
;   float t[8], u[4], v2[2];
; #pragma unroll
;   for (int j = 0; j < 8; ++j) { float keep = b3 ? yp[j + 8] : yp[j], send = b3 ? yp[j] : yp[j + 8]; t[j] = keep + dpp_get<0x140>(send); }
; #pragma unroll
;   for (int j = 0; j < 4; ++j) { float keep = b2 ? t[j + 4] : t[j], send = b2 ? t[j] : t[j + 4]; u[j] = keep + dpp_get<0x141>(send); }
; #pragma unroll
;   for (int j = 0; j < 2; ++j) { float keep = b1 ? u[j + 2] : u[j], send = b1 ? u[j] : u[j + 2]; v2[j] = keep + dpp_get<0x4E>(send); }
;   { float keep = b0 ? v2[1] : v2[0], send = b0 ? v2[0] : v2[1]; ys = keep + dpp_get<0xB1>(send); }
; }
; DI void scan_job(const int tid_, const Params& p, int l, int job, char* s0, char* s1, char* s2) {
;     ...
;     Y[(size_t)(tok0 + c * 16 + kg) * 512 + h * 64 + row] = ys;
;     if (c + 1 < nchunks) scan_lstore(tid_, A, buf1);
	v_pk_mul_f32 v[68:69], v[120:121], v[74:75] op_sel_hi:[1,0]
	v_pk_mul_f32 v[78:79], v[122:123], v[74:75] op_sel_hi:[1,0]
	v_add_f32_dpp v44, v44, v44 row_ror:1 row_mask:0xf bank_mask:0xf bound_ctrl:1
	v_pk_fma_f32 v[26:27], v[44:45], v[108:109], v[26:27] op_sel_hi:[0,1,1]
	v_pk_fma_f32 v[28:29], v[44:45], v[110:111], v[28:29] op_sel_hi:[0,1,1]
	v_mul_f32_e32 v44, v104, v26
	v_fmac_f32_e32 v44, v27, v105
	v_fmac_f32_e32 v44, v28, v106
	v_fmac_f32_e32 v44, v29, v107
	s_waitcnt lgkmcnt(12)
	v_mul_f32_e32 v66, v124, v26
	v_fmac_f32_e32 v66, v27, v125
	v_add_f32_dpp v44, v44, v44 row_ror:8 row_mask:0xf bank_mask:0xf bound_ctrl:1
	v_fmac_f32_e32 v66, v28, v126
	v_pk_fma_f32 v[26:27], v[26:27], v[96:97], v[68:69]
	v_add_f32_dpp v44, v44, v44 row_ror:4 row_mask:0xf bank_mask:0xf bound_ctrl:1
	v_fmac_f32_e32 v66, v29, v127
	v_pk_fma_f32 v[28:29], v[28:29], v[98:99], v[78:79]
	v_add_f32_dpp v44, v44, v44 row_ror:2 row_mask:0xf bank_mask:0xf bound_ctrl:1
	s_waitcnt lgkmcnt(3)
	v_pk_mul_f32 v[72:73], v[162:163], v[202:203] op_sel_hi:[1,0]
	v_pk_mul_f32 v[118:119], v[164:165], v[202:203] op_sel_hi:[1,0]
	v_add_f32_dpp v44, v44, v44 row_ror:1 row_mask:0xf bank_mask:0xf bound_ctrl:1
	v_pk_fma_f32 v[26:27], v[44:45], v[112:113], v[26:27] op_sel_hi:[0,1,1]
	v_pk_fma_f32 v[28:29], v[44:45], v[114:115], v[28:29] op_sel_hi:[0,1,1]
	v_mul_f32_e32 v44, v146, v26
	v_fmac_f32_e32 v44, v27, v147
	v_fmac_f32_e32 v44, v28, v148
	v_fmac_f32_e32 v44, v29, v149
	v_mul_f32_e32 v67, v128, v26
	v_fmac_f32_e32 v67, v27, v129
	v_add_f32_dpp v44, v44, v44 row_ror:8 row_mask:0xf bank_mask:0xf bound_ctrl:1
	v_fmac_f32_e32 v67, v28, v130
	v_pk_fma_f32 v[26:27], v[26:27], v[138:139], v[72:73]
	v_add_f32_dpp v44, v44, v44 row_ror:4 row_mask:0xf bank_mask:0xf bound_ctrl:1
	v_fmac_f32_e32 v67, v29, v131
	v_pk_fma_f32 v[28:29], v[28:29], v[140:141], v[118:119]
	v_add_f32_dpp v44, v44, v44 row_ror:2 row_mask:0xf bank_mask:0xf bound_ctrl:1
	v_mov_b32_e32 v46, v203
	s_waitcnt lgkmcnt(2)
	v_pk_mul_f32 v[74:75], v[172:173], v[46:47] op_sel_hi:[1,0]
	v_add_f32_dpp v44, v44, v44 row_ror:1 row_mask:0xf bank_mask:0xf bound_ctrl:1
	v_pk_fma_f32 v[26:27], v[44:45], v[154:155], v[26:27] op_sel_hi:[0,1,1]
	v_pk_fma_f32 v[28:29], v[44:45], v[156:157], v[28:29] op_sel_hi:[0,1,1]
	v_mul_f32_e32 v44, v150, v26
	v_fmac_f32_e32 v44, v27, v151
	v_fmac_f32_e32 v44, v28, v152
	v_fmac_f32_e32 v44, v29, v153
	s_waitcnt lgkmcnt(1)
	v_mul_f32_e32 v68, v182, v26
	v_fmac_f32_e32 v68, v27, v183
	v_add_f32_dpp v44, v44, v44 row_ror:8 row_mask:0xf bank_mask:0xf bound_ctrl:1
	v_pk_mul_f32 v[64:65], v[174:175], v[46:47] op_sel_hi:[1,0]
	v_cndmask_b32_e64 v46, v206, v0, s[40:41]
	v_add_f32_dpp v44, v44, v44 row_ror:4 row_mask:0xf bank_mask:0xf bound_ctrl:1
	v_cndmask_b32_e64 v0, v0, v206, s[40:41]
	v_fmac_f32_e32 v68, v28, v184
	v_add_f32_dpp v44, v44, v44 row_ror:2 row_mask:0xf bank_mask:0xf bound_ctrl:1
	v_pk_fma_f32 v[26:27], v[26:27], v[142:143], v[74:75]
	v_add_f32_dpp v0, v0, v46 row_mirror row_mask:0xf bank_mask:0xf bound_ctrl:1
	v_add_f32_dpp v44, v44, v44 row_ror:1 row_mask:0xf bank_mask:0xf bound_ctrl:1
	v_cndmask_b32_e64 v46, v207, v47, s[40:41]
	v_cndmask_b32_e64 v47, v47, v207, s[40:41]
	v_fmac_f32_e32 v68, v29, v185
	v_pk_fma_f32 v[26:27], v[44:45], v[158:159], v[26:27] op_sel_hi:[0,1,1]
	v_pk_fma_f32 v[28:29], v[28:29], v[144:145], v[64:65]
	v_add_f32_dpp v46, v47, v46 row_mirror row_mask:0xf bank_mask:0xf bound_ctrl:1
	v_cndmask_b32_e64 v47, v76, v62, s[40:41]
	v_cndmask_b32_e64 v62, v62, v76, s[40:41]
	v_pk_fma_f32 v[28:29], v[44:45], v[160:161], v[28:29] op_sel_hi:[0,1,1]
	s_waitcnt lgkmcnt(0)
	v_mul_f32_e32 v44, v186, v26
	v_add_f32_dpp v47, v62, v47 row_mirror row_mask:0xf bank_mask:0xf bound_ctrl:1
	v_cndmask_b32_e64 v62, v45, v63, s[40:41]
	v_cndmask_b32_e64 v45, v63, v45, s[40:41]
	v_fmac_f32_e32 v44, v27, v187
	v_cndmask_b32_e64 v63, v135, v66, s[40:41]
	v_add_f32_dpp v45, v45, v62 row_mirror row_mask:0xf bank_mask:0xf bound_ctrl:1
	v_cndmask_b32_e64 v62, v66, v135, s[40:41]
	v_fmac_f32_e32 v44, v28, v188
	v_cndmask_b32_e64 v64, v181, v67, s[40:41]
	v_add_f32_dpp v62, v63, v62 row_mirror row_mask:0xf bank_mask:0xf bound_ctrl:1
	v_cndmask_b32_e64 v63, v67, v181, s[40:41]
	v_fmac_f32_e32 v44, v29, v189
	v_cndmask_b32_e64 v65, v195, v68, s[40:41]
	v_add_f32_dpp v63, v64, v63 row_mirror row_mask:0xf bank_mask:0xf bound_ctrl:1
	v_cndmask_b32_e64 v64, v68, v195, s[40:41]
	s_nop 1
	v_add_f32_dpp v64, v65, v64 row_mirror row_mask:0xf bank_mask:0xf bound_ctrl:1
	v_cndmask_b32_e64 v65, v44, v204, s[40:41]
	v_cndmask_b32_e64 v44, v204, v44, s[40:41]
	s_nop 1
	v_add_f32_dpp v44, v44, v65 row_mirror row_mask:0xf bank_mask:0xf bound_ctrl:1
	v_cndmask_b32_e64 v65, v62, v0, s[42:43]
	v_cndmask_b32_e64 v0, v0, v62, s[42:43]
	v_cndmask_b32_e64 v62, v63, v46, s[42:43]
	v_cndmask_b32_e64 v46, v46, v63, s[42:43]
	v_add_f32_dpp v0, v0, v65 row_half_mirror row_mask:0xf bank_mask:0xf bound_ctrl:1
	s_nop 0
	v_add_f32_dpp v46, v46, v62 row_half_mirror row_mask:0xf bank_mask:0xf bound_ctrl:1
	v_cndmask_b32_e64 v62, v64, v47, s[42:43]
	v_cndmask_b32_e64 v47, v47, v64, s[42:43]
	s_nop 1
	v_add_f32_dpp v47, v47, v62 row_half_mirror row_mask:0xf bank_mask:0xf bound_ctrl:1
	v_cndmask_b32_e64 v62, v44, v45, s[42:43]
	v_cndmask_b32_e64 v44, v45, v44, s[42:43]
	v_cndmask_b32_e64 v45, v47, v0, s[44:45]
	v_cndmask_b32_e64 v0, v0, v47, s[44:45]
	v_add_f32_dpp v44, v44, v62 row_half_mirror row_mask:0xf bank_mask:0xf bound_ctrl:1
	s_nop 0
	v_add_f32_dpp v0, v0, v45 quad_perm:[2,3,0,1] row_mask:0xf bank_mask:0xf bound_ctrl:1
	v_cndmask_b32_e64 v45, v44, v46, s[44:45]
	v_cndmask_b32_e64 v44, v46, v44, s[44:45]
	s_nop 1
	v_add_f32_dpp v44, v44, v45 quad_perm:[2,3,0,1] row_mask:0xf bank_mask:0xf bound_ctrl:1
	v_cndmask_b32_e64 v45, v44, v0, s[46:47]
	v_cndmask_b32_e64 v0, v0, v44, s[46:47]
	v_add_u32_e32 v44, s38, v43
	s_nop 0
	v_add_f32_dpp v0, v0, v45 quad_perm:[1,0,3,2] row_mask:0xf bank_mask:0xf bound_ctrl:1
	v_ashrrev_i32_e32 v45, 31, v44
	v_lshlrev_b64 v[46:47], 11, v[44:45]
	v_lshl_add_u64 v[46:47], v[36:37], 0, v[46:47]
	s_waitcnt lgkmcnt(0)
	flat_store_dword v[46:47], v0
	s_cbranch_scc1 .LBB0_188
	s_waitcnt vmcnt(1)
	v_lshlrev_b32_e32 v0, 16, v50
	v_lshlrev_b32_e32 v62, 16, v6
	v_and_b32_e32 v63, 0xffff0000, v6
	v_lshlrev_b32_e32 v64, 16, v7
	v_and_b32_e32 v65, 0xffff0000, v7
	ds_write_b128 v57, v[2:5]
	ds_write_b32 v58, v0 offset:20480
	ds_write_b128 v59, v[62:65] offset:4096
	v_lshlrev_b32_e32 v62, 16, v8
	v_and_b32_e32 v63, 0xffff0000, v8
	v_lshlrev_b32_e32 v64, 16, v9
	v_and_b32_e32 v65, 0xffff0000, v9
	ds_write_b128 v59, v[62:65] offset:4112
	v_lshlrev_b32_e32 v62, 16, v10
	v_and_b32_e32 v63, 0xffff0000, v10
	v_lshlrev_b32_e32 v64, 16, v11
	v_and_b32_e32 v65, 0xffff0000, v11
	ds_write_b128 v59, v[62:65] offset:12288
	v_lshlrev_b32_e32 v62, 16, v12
	v_and_b32_e32 v63, 0xffff0000, v12
	v_lshlrev_b32_e32 v64, 16, v13
	v_and_b32_e32 v65, 0xffff0000, v13
	ds_write_b128 v59, v[62:65] offset:12304

; DI void scan_chunk(const float* buf, f32x4& S, int w, int rw, int kg, float& ys) {
;   float yp[16];
; #pragma unroll
;   for (int s = 0; s < 16; ++s) {
;     const float* b = buf + s * 64 + kg * 4;
;     f32x4 d = *(const f32x4*)(b), n = *(const f32x4*)(b + 1024), a = *(const f32x4*)(b + 2048), k = *(const f32x4*)(b + 3072),
;           r = *(const f32x4*)(b + 4096);
;     float vv = buf[5120 + s * 16 + w * 4 + rw];
;     float pp = S[0] * n[0];
;     pp = fmaf(S[1], n[1], pp); pp = fmaf(S[2], n[2], pp); pp = fmaf(S[3], n[3], pp);
;     float sa = row_allreduce(pp);
; #pragma unroll
;     for (int e = 0; e < 4; ++e) S[e] = fmaf(sa, a[e], fmaf(S[e], d[e], vv * k[e]));
;     float y = S[0] * r[0];
;     y = fmaf(S[1], r[1], y); y = fmaf(S[2], r[2], y); y = fmaf(S[3], r[3], y);
;     yp[s] = y;
;   }
.LBB0_191:
	ds_read_b128 v[62:65], v56 offset:4096
	v_add_u32_e32 v45, 0x5000, v60
	ds_read_b128 v[66:69], v56 offset:4352
	ds_read2_b32 v[46:47], v45 offset1:16
	s_andn2_b64 vcc, exec, s[30:31]
	s_waitcnt lgkmcnt(2)
	v_mul_f32_e32 v0, v26, v62
	v_fmac_f32_e32 v0, v27, v63
	v_fmac_f32_e32 v0, v28, v64
	v_fmac_f32_e32 v0, v29, v65
	ds_read_b128 v[62:65], v56
	ds_read_b128 v[70:73], v56 offset:256
	ds_read_b128 v[74:77], v56 offset:8192
	ds_read_b128 v[78:81], v56 offset:8448
	ds_read_b128 v[82:85], v56 offset:12288
	ds_read_b128 v[86:89], v56 offset:12544
	ds_read_b128 v[90:93], v56 offset:16384
	ds_read_b128 v[94:97], v56 offset:16640
	ds_read2_b32 v[182:183], v45 offset0:32 offset1:48
	ds_read_b128 v[98:101], v56 offset:512
	ds_read_b128 v[102:105], v56 offset:768
	ds_read_b128 v[106:109], v56 offset:4608
	ds_read_b128 v[110:113], v56 offset:4864
	ds_read_b128 v[114:117], v56 offset:8704
	ds_read_b128 v[118:121], v56 offset:8960
	ds_read_b128 v[122:125], v56 offset:12800
	ds_read_b128 v[126:129], v56 offset:13056
	ds_read_b128 v[138:141], v56 offset:16896
	ds_read_b128 v[142:145], v56 offset:17152
	ds_read_b128 v[146:149], v56 offset:1024
	ds_read_b128 v[150:153], v56 offset:5120
	ds_read_b128 v[154:157], v56 offset:9216
	ds_read_b128 v[158:161], v56 offset:13312
	ds_read_b128 v[162:165], v56 offset:17408
	ds_read2_b32 v[184:185], v45 offset0:64 offset1:80
	v_add_f32_dpp v0, v0, v0 row_ror:8 row_mask:0xf bank_mask:0xf bound_ctrl:1
	s_waitcnt lgkmcnt(15)
	v_pk_mul_f32 v[82:83], v[82:83], v[46:47] op_sel_hi:[1,0]
	ds_read_b128 v[172:175], v56 offset:13568
	v_add_f32_dpp v0, v0, v0 row_ror:4 row_mask:0xf bank_mask:0xf bound_ctrl:1
	v_pk_fma_f32 v[26:27], v[26:27], v[62:63], v[82:83]
	v_mov_b32_e32 v62, v47
	v_add_f32_dpp v0, v0, v0 row_ror:2 row_mask:0xf bank_mask:0xf bound_ctrl:1
	v_pk_mul_f32 v[46:47], v[84:85], v[46:47] op_sel_hi:[1,0]
	s_waitcnt lgkmcnt(1)
	v_pk_mul_f32 v[82:83], v[158:159], v[184:185] op_sel_hi:[1,0]
	v_add_f32_dpp v130, v0, v0 row_ror:1 row_mask:0xf bank_mask:0xf bound_ctrl:1
	v_pk_fma_f32 v[26:27], v[130:131], v[74:75], v[26:27] op_sel_hi:[0,1,1]
	v_mul_f32_e32 v63, v66, v26
	v_pk_fma_f32 v[28:29], v[28:29], v[64:65], v[46:47]
	v_fmac_f32_e32 v63, v27, v67
	v_pk_fma_f32 v[28:29], v[130:131], v[76:77], v[28:29] op_sel_hi:[0,1,1]
	v_mul_f32_e32 v0, v90, v26
	v_pk_mul_f32 v[66:67], v[86:87], v[62:63] op_sel_hi:[1,0]
	v_pk_mul_f32 v[46:47], v[88:89], v[62:63] op_sel_hi:[1,0]
	v_fmac_f32_e32 v63, v28, v68
	v_fmac_f32_e32 v0, v27, v91
	v_fmac_f32_e32 v63, v29, v69
	v_pk_fma_f32 v[46:47], v[28:29], v[72:73], v[46:47]
	v_fmac_f32_e32 v0, v28, v92
	v_add_f32_dpp v28, v63, v63 row_ror:8 row_mask:0xf bank_mask:0xf bound_ctrl:1
	v_pk_fma_f32 v[26:27], v[26:27], v[70:71], v[66:67]
	v_fmac_f32_e32 v0, v29, v93
	v_add_f32_dpp v28, v28, v28 row_ror:4 row_mask:0xf bank_mask:0xf bound_ctrl:1
	v_pk_mul_f32 v[66:67], v[122:123], v[182:183] op_sel_hi:[1,0]
	v_pk_mul_f32 v[64:65], v[124:125], v[182:183] op_sel_hi:[1,0]
	v_add_f32_dpp v28, v28, v28 row_ror:2 row_mask:0xf bank_mask:0xf bound_ctrl:1
	v_mov_b32_e32 v70, v183
	v_pk_mul_f32 v[74:75], v[126:127], v[70:71] op_sel_hi:[1,0]
	v_add_f32_dpp v28, v28, v28 row_ror:1 row_mask:0xf bank_mask:0xf bound_ctrl:1
	v_pk_fma_f32 v[26:27], v[28:29], v[78:79], v[26:27] op_sel_hi:[0,1,1]
	v_pk_fma_f32 v[28:29], v[28:29], v[80:81], v[46:47] op_sel_hi:[0,1,1]
	v_mul_f32_e32 v46, v106, v26
	v_fmac_f32_e32 v46, v27, v107
	v_fmac_f32_e32 v46, v28, v108
	v_fmac_f32_e32 v46, v29, v109
	v_mul_f32_e32 v62, v94, v26
	v_fmac_f32_e32 v62, v27, v95
	v_add_f32_dpp v46, v46, v46 row_ror:8 row_mask:0xf bank_mask:0xf bound_ctrl:1
	v_fmac_f32_e32 v62, v28, v96
	v_pk_fma_f32 v[26:27], v[26:27], v[98:99], v[66:67]
	v_add_f32_dpp v46, v46, v46 row_ror:4 row_mask:0xf bank_mask:0xf bound_ctrl:1
	v_fmac_f32_e32 v62, v29, v97
	v_pk_fma_f32 v[28:29], v[28:29], v[100:101], v[64:65]
	v_add_f32_dpp v46, v46, v46 row_ror:2 row_mask:0xf bank_mask:0xf bound_ctrl:1
	v_pk_mul_f32 v[70:71], v[128:129], v[70:71] op_sel_hi:[1,0]
	ds_read_b128 v[66:69], v56 offset:1280
	v_add_f32_dpp v46, v46, v46 row_ror:1 row_mask:0xf bank_mask:0xf bound_ctrl:1
	v_pk_fma_f32 v[26:27], v[46:47], v[114:115], v[26:27] op_sel_hi:[0,1,1]
	v_pk_fma_f32 v[28:29], v[46:47], v[116:117], v[28:29] op_sel_hi:[0,1,1]
	v_mul_f32_e32 v46, v110, v26
	v_fmac_f32_e32 v46, v27, v111
	v_fmac_f32_e32 v46, v28, v112
	v_fmac_f32_e32 v46, v29, v113
	v_mul_f32_e32 v63, v138, v26
	v_fmac_f32_e32 v63, v27, v139
	v_add_f32_dpp v46, v46, v46 row_ror:8 row_mask:0xf bank_mask:0xf bound_ctrl:1
	v_pk_fma_f32 v[26:27], v[26:27], v[102:103], v[74:75]
	v_fmac_f32_e32 v63, v28, v140
	v_add_f32_dpp v46, v46, v46 row_ror:4 row_mask:0xf bank_mask:0xf bound_ctrl:1
	v_fmac_f32_e32 v63, v29, v141
	s_nop 0
	v_add_f32_dpp v46, v46, v46 row_ror:2 row_mask:0xf bank_mask:0xf bound_ctrl:1
	s_nop 1
	v_add_f32_dpp v46, v46, v46 row_ror:1 row_mask:0xf bank_mask:0xf bound_ctrl:1
	v_pk_fma_f32 v[72:73], v[46:47], v[118:119], v[26:27] op_sel_hi:[0,1,1]
	v_pk_fma_f32 v[26:27], v[28:29], v[104:105], v[70:71]
	v_mul_f32_e32 v65, v150, v72
	v_pk_fma_f32 v[46:47], v[46:47], v[120:121], v[26:27] op_sel_hi:[0,1,1]
	v_fmac_f32_e32 v65, v73, v151
	v_fmac_f32_e32 v65, v46, v152
	v_fmac_f32_e32 v65, v47, v153
	ds_read_b128 v[26:29], v56 offset:5376
	v_mul_f32_e32 v64, v142, v72
	v_add_f32_dpp v65, v65, v65 row_ror:8 row_mask:0xf bank_mask:0xf bound_ctrl:1
	v_fmac_f32_e32 v64, v73, v143
	v_pk_fma_f32 v[76:77], v[72:73], v[146:147], v[82:83]
	v_add_f32_dpp v65, v65, v65 row_ror:4 row_mask:0xf bank_mask:0xf bound_ctrl:1
	v_fmac_f32_e32 v64, v46, v144
	v_fmac_f32_e32 v64, v47, v145
	v_add_f32_dpp v65, v65, v65 row_ror:2 row_mask:0xf bank_mask:0xf bound_ctrl:1
	ds_read_b128 v[70:73], v56 offset:9472
	s_nop 0
	v_add_f32_dpp v74, v65, v65 row_ror:1 row_mask:0xf bank_mask:0xf bound_ctrl:1
	v_pk_fma_f32 v[130:131], v[74:75], v[154:155], v[76:77] op_sel_hi:[0,1,1]
	v_pk_mul_f32 v[76:77], v[160:161], v[184:185] op_sel_hi:[1,0]
	s_waitcnt lgkmcnt(1)
; DI void scan_chunk(const float* buf, f32x4& S, int w, int rw, int kg, float& ys) {
;     ...
;   for (int s = 0; s < 16; ++s) {
;     const float* b = buf + s * 64 + kg * 4;
;     f32x4 d = *(const f32x4*)(b), n = *(const f32x4*)(b + 1024), a = *(const f32x4*)(b + 2048), k = *(const f32x4*)(b + 3072),
;           r = *(const f32x4*)(b + 4096);
;     float vv = buf[5120 + s * 16 + w * 4 + rw];
;     float pp = S[0] * n[0];
;     pp = fmaf(S[1], n[1], pp); pp = fmaf(S[2], n[2], pp); pp = fmaf(S[3], n[3], pp);
;     float sa = row_allreduce(pp);
; #pragma unroll
;     for (int e = 0; e < 4; ++e) S[e] = fmaf(sa, a[e], fmaf(S[e], d[e], vv * k[e]));
;     float y = S[0] * r[0];
;     y = fmaf(S[1], r[1], y); y = fmaf(S[2], r[2], y); y = fmaf(S[3], r[3], y);
;     yp[s] = y;
;   }
	v_mul_f32_e32 v26, v26, v130
	v_pk_fma_f32 v[46:47], v[46:47], v[148:149], v[76:77]
	v_fmac_f32_e32 v26, v131, v27
	v_pk_fma_f32 v[186:187], v[74:75], v[156:157], v[46:47] op_sel_hi:[0,1,1]
	v_fmac_f32_e32 v26, v186, v28
	v_fmac_f32_e32 v26, v187, v29
	ds_read_b128 v[74:77], v56 offset:17664
	v_mul_f32_e32 v65, v162, v130
	v_add_f32_dpp v26, v26, v26 row_ror:8 row_mask:0xf bank_mask:0xf bound_ctrl:1
	v_fmac_f32_e32 v65, v131, v163
	v_fmac_f32_e32 v65, v186, v164
	v_add_f32_dpp v26, v26, v26 row_ror:4 row_mask:0xf bank_mask:0xf bound_ctrl:1
	v_fmac_f32_e32 v65, v187, v165
	s_nop 0
	v_add_f32_dpp v26, v26, v26 row_ror:2 row_mask:0xf bank_mask:0xf bound_ctrl:1
	s_nop 1
	v_add_f32_dpp v188, v26, v26 row_ror:1 row_mask:0xf bank_mask:0xf bound_ctrl:1
	v_mov_b32_e32 v26, v185
	v_pk_mul_f32 v[190:191], v[172:173], v[26:27] op_sel_hi:[1,0]
	v_pk_mul_f32 v[192:193], v[174:175], v[26:27] op_sel_hi:[1,0]
	v_pk_fma_f32 v[66:67], v[130:131], v[66:67], v[190:191]
	ds_read2_b32 v[194:195], v45 offset0:96 offset1:112
	ds_read_b128 v[78:81], v56 offset:1536
	ds_read_b128 v[82:85], v56 offset:1792
	ds_read_b128 v[86:89], v56 offset:5632
	ds_read_b128 v[90:93], v56 offset:5888
	ds_read_b128 v[94:97], v56 offset:9728
	ds_read_b128 v[98:101], v56 offset:9984
	ds_read_b128 v[102:105], v56 offset:13824
	ds_read_b128 v[106:109], v56 offset:14080
	ds_read_b128 v[110:113], v56 offset:17920
	ds_read_b128 v[114:117], v56 offset:18176
	ds_read2_b32 v[196:197], v45 offset0:128 offset1:144
	ds_read_b128 v[118:121], v56 offset:2048
	ds_read_b128 v[122:125], v56 offset:2304
	ds_read_b128 v[126:129], v56 offset:6144
	ds_read_b128 v[138:141], v56 offset:6400
	ds_read_b128 v[142:145], v56 offset:10240
	ds_read_b128 v[146:149], v56 offset:10496
	ds_read_b128 v[150:153], v56 offset:14336
	ds_read_b128 v[154:157], v56 offset:14592
	ds_read_b128 v[158:161], v56 offset:18432
	ds_read_b128 v[162:165], v56 offset:18688
	ds_read_b128 v[26:29], v56 offset:2560
	ds_read_b128 v[172:175], v56 offset:6656
	ds_read_b128 v[182:185], v56 offset:14848
	ds_read2_b32 v[46:47], v45 offset0:160 offset1:176
	s_waitcnt lgkmcnt(15)
	v_pk_fma_f32 v[66:67], v[188:189], v[70:71], v[66:67] op_sel_hi:[0,1,1]
	v_pk_fma_f32 v[68:69], v[186:187], v[68:69], v[192:193]
	s_waitcnt lgkmcnt(15)
	v_mul_f32_e32 v130, v86, v66
	v_pk_fma_f32 v[72:73], v[188:189], v[72:73], v[68:69] op_sel_hi:[0,1,1]
	v_fmac_f32_e32 v130, v67, v87
	v_mul_f32_e32 v131, v74, v66
	v_fmac_f32_e32 v130, v72, v88
	s_waitcnt lgkmcnt(15)
	v_pk_mul_f32 v[68:69], v[104:105], v[194:195] op_sel_hi:[1,0]
	v_fmac_f32_e32 v131, v67, v75
	v_fmac_f32_e32 v130, v73, v89
	v_pk_fma_f32 v[80:81], v[72:73], v[80:81], v[68:69]
	v_fmac_f32_e32 v131, v72, v76
	v_add_f32_dpp v72, v130, v130 row_ror:8 row_mask:0xf bank_mask:0xf bound_ctrl:1
	v_pk_mul_f32 v[70:71], v[102:103], v[194:195] op_sel_hi:[1,0]
	v_fmac_f32_e32 v131, v73, v77
	v_add_f32_dpp v72, v72, v72 row_ror:4 row_mask:0xf bank_mask:0xf bound_ctrl:1
	v_pk_fma_f32 v[70:71], v[66:67], v[78:79], v[70:71]
	v_mov_b32_e32 v68, v195
	v_add_f32_dpp v72, v72, v72 row_ror:2 row_mask:0xf bank_mask:0xf bound_ctrl:1
	s_waitcnt lgkmcnt(15)
	v_pk_mul_f32 v[74:75], v[106:107], v[68:69] op_sel_hi:[1,0]
	v_pk_mul_f32 v[104:105], v[108:109], v[68:69] op_sel_hi:[1,0]
	v_add_f32_dpp v72, v72, v72 row_ror:1 row_mask:0xf bank_mask:0xf bound_ctrl:1
	v_pk_fma_f32 v[70:71], v[72:73], v[94:95], v[70:71] op_sel_hi:[0,1,1]
	v_mul_f32_e32 v76, v90, v70
	v_pk_fma_f32 v[72:73], v[72:73], v[96:97], v[80:81] op_sel_hi:[0,1,1]
	v_fmac_f32_e32 v76, v71, v91
	v_fmac_f32_e32 v76, v72, v92
	v_fmac_f32_e32 v76, v73, v93
	s_waitcnt lgkmcnt(15)
	v_mul_f32_e32 v135, v110, v70
	v_fmac_f32_e32 v135, v71, v111
	v_add_f32_dpp v76, v76, v76 row_ror:8 row_mask:0xf bank_mask:0xf bound_ctrl:1
	v_pk_fma_f32 v[70:71], v[70:71], v[82:83], v[74:75]
	v_fmac_f32_e32 v135, v72, v112
	v_add_f32_dpp v76, v76, v76 row_ror:4 row_mask:0xf bank_mask:0xf bound_ctrl:1
	v_fmac_f32_e32 v135, v73, v113
	v_pk_fma_f32 v[72:73], v[72:73], v[84:85], v[104:105]
	v_add_f32_dpp v76, v76, v76 row_ror:2 row_mask:0xf bank_mask:0xf bound_ctrl:1
	s_waitcnt lgkmcnt(7)
	v_pk_mul_f32 v[78:79], v[150:151], v[196:197] op_sel_hi:[1,0]
	v_pk_mul_f32 v[108:109], v[152:153], v[196:197] op_sel_hi:[1,0]
	v_add_f32_dpp v76, v76, v76 row_ror:1 row_mask:0xf bank_mask:0xf bound_ctrl:1
	v_pk_fma_f32 v[70:71], v[76:77], v[98:99], v[70:71] op_sel_hi:[0,1,1]
	v_mul_f32_e32 v74, v126, v70
	v_pk_fma_f32 v[72:73], v[76:77], v[100:101], v[72:73] op_sel_hi:[0,1,1]
	v_fmac_f32_e32 v74, v71, v127
	v_fmac_f32_e32 v74, v72, v128
	v_fmac_f32_e32 v74, v73, v129
	v_mul_f32_e32 v181, v114, v70
	v_fmac_f32_e32 v181, v71, v115
	v_add_f32_dpp v74, v74, v74 row_ror:8 row_mask:0xf bank_mask:0xf bound_ctrl:1
	v_fmac_f32_e32 v181, v72, v116
	v_pk_fma_f32 v[70:71], v[70:71], v[118:119], v[78:79]
	v_add_f32_dpp v74, v74, v74 row_ror:4 row_mask:0xf bank_mask:0xf bound_ctrl:1
	v_fmac_f32_e32 v181, v73, v117
	v_pk_fma_f32 v[72:73], v[72:73], v[120:121], v[108:109]
	v_add_f32_dpp v74, v74, v74 row_ror:2 row_mask:0xf bank_mask:0xf bound_ctrl:1
	v_mov_b32_e32 v152, v197
	s_waitcnt lgkmcnt(6)
	v_pk_mul_f32 v[86:87], v[154:155], v[152:153] op_sel_hi:[1,0]
	v_add_f32_dpp v74, v74, v74 row_ror:1 row_mask:0xf bank_mask:0xf bound_ctrl:1
	v_pk_fma_f32 v[70:71], v[74:75], v[142:143], v[70:71] op_sel_hi:[0,1,1]
	v_pk_fma_f32 v[72:73], v[74:75], v[144:145], v[72:73] op_sel_hi:[0,1,1]
	v_mul_f32_e32 v74, v138, v70
	v_fmac_f32_e32 v74, v71, v139
	v_fmac_f32_e32 v74, v72, v140
	v_fmac_f32_e32 v74, v73, v141
	s_waitcnt lgkmcnt(5)
; DI void scan_chunk(const float* buf, f32x4& S, int w, int rw, int kg, float& ys) {
;     ...
;   for (int s = 0; s < 16; ++s) {
;     const float* b = buf + s * 64 + kg * 4;
;     f32x4 d = *(const f32x4*)(b), n = *(const f32x4*)(b + 1024), a = *(const f32x4*)(b + 2048), k = *(const f32x4*)(b + 3072),
;           r = *(const f32x4*)(b + 4096);
;     float vv = buf[5120 + s * 16 + w * 4 + rw];
;     float pp = S[0] * n[0];
;     pp = fmaf(S[1], n[1], pp); pp = fmaf(S[2], n[2], pp); pp = fmaf(S[3], n[3], pp);
;     float sa = row_allreduce(pp);
; #pragma unroll
;     for (int e = 0; e < 4; ++e) S[e] = fmaf(sa, a[e], fmaf(S[e], d[e], vv * k[e]));
;     float y = S[0] * r[0];
;     y = fmaf(S[1], r[1], y); y = fmaf(S[2], r[2], y); y = fmaf(S[3], r[3], y);
;     yp[s] = y;
;   }
	v_mul_f32_e32 v198, v158, v70
	v_pk_mul_f32 v[156:157], v[156:157], v[152:153] op_sel_hi:[1,0]
	v_add_f32_dpp v74, v74, v74 row_ror:8 row_mask:0xf bank_mask:0xf bound_ctrl:1
	v_fmac_f32_e32 v198, v71, v159
	v_pk_fma_f32 v[70:71], v[70:71], v[122:123], v[86:87]
	v_add_f32_dpp v74, v74, v74 row_ror:4 row_mask:0xf bank_mask:0xf bound_ctrl:1
	v_fmac_f32_e32 v198, v72, v160
	v_fmac_f32_e32 v198, v73, v161
	v_add_f32_dpp v74, v74, v74 row_ror:2 row_mask:0xf bank_mask:0xf bound_ctrl:1
	s_waitcnt lgkmcnt(0)
	v_pk_mul_f32 v[102:103], v[182:183], v[46:47] op_sel_hi:[1,0]
	ds_read_b128 v[66:69], v56 offset:15104
	v_add_f32_dpp v74, v74, v74 row_ror:1 row_mask:0xf bank_mask:0xf bound_ctrl:1
	v_pk_fma_f32 v[78:79], v[74:75], v[146:147], v[70:71] op_sel_hi:[0,1,1]
	v_pk_fma_f32 v[70:71], v[72:73], v[124:125], v[156:157]
	v_mul_f32_e32 v199, v162, v78
	v_pk_fma_f32 v[80:81], v[74:75], v[148:149], v[70:71] op_sel_hi:[0,1,1]
	v_mul_f32_e32 v74, v172, v78
	v_fmac_f32_e32 v74, v79, v173
	v_fmac_f32_e32 v74, v80, v174
	v_fmac_f32_e32 v74, v81, v175
	ds_read_b128 v[70:73], v56 offset:6912
	v_fmac_f32_e32 v199, v79, v163
	v_add_f32_dpp v74, v74, v74 row_ror:8 row_mask:0xf bank_mask:0xf bound_ctrl:1
	v_fmac_f32_e32 v199, v80, v164
	v_pk_fma_f32 v[190:191], v[78:79], v[26:27], v[102:103]
	v_add_f32_dpp v74, v74, v74 row_ror:4 row_mask:0xf bank_mask:0xf bound_ctrl:1
	v_pk_mul_f32 v[26:27], v[184:185], v[46:47] op_sel_hi:[1,0]
	v_fmac_f32_e32 v199, v81, v165
	v_add_f32_dpp v74, v74, v74 row_ror:2 row_mask:0xf bank_mask:0xf bound_ctrl:1
	v_pk_fma_f32 v[192:193], v[80:81], v[28:29], v[26:27]
	v_mov_b32_e32 v46, v47
	v_add_f32_dpp v130, v74, v74 row_ror:1 row_mask:0xf bank_mask:0xf bound_ctrl:1
	ds_read_b128 v[74:77], v56 offset:2816
	ds_read_b128 v[26:29], v56 offset:10752
	ds_read_b128 v[78:81], v56 offset:11008
	ds_read_b128 v[82:85], v56 offset:18944
	ds_read_b128 v[86:89], v56 offset:19200
	ds_read2_b32 v[194:195], v45 offset0:192 offset1:208
	ds_read_b128 v[90:93], v56 offset:3072
	ds_read_b128 v[94:97], v56 offset:3328
	ds_read_b128 v[98:101], v56 offset:7168
	ds_read_b128 v[102:105], v56 offset:7424
	ds_read_b128 v[106:109], v56 offset:11264
	ds_read_b128 v[110:113], v56 offset:11520
	ds_read_b128 v[114:117], v56 offset:15360
	ds_read_b128 v[118:121], v56 offset:15616
	ds_read_b128 v[122:125], v56 offset:19456
	ds_read_b128 v[126:129], v56 offset:19712
	ds_read2_b32 v[196:197], v45 offset0:224 offset1:240
	ds_read_b128 v[138:141], v56 offset:3584
	ds_read_b128 v[142:145], v56 offset:3840
	ds_read_b128 v[146:149], v56 offset:7680
	ds_read_b128 v[150:153], v56 offset:7936
	ds_read_b128 v[154:157], v56 offset:11776
	ds_read_b128 v[158:161], v56 offset:12032
	ds_read_b128 v[162:165], v56 offset:15872
	ds_read_b128 v[172:175], v56 offset:16128
	ds_read_b128 v[182:185], v56 offset:19968
	ds_read_b128 v[186:189], v56 offset:20224
	s_waitcnt lgkmcnt(15)
	v_pk_fma_f32 v[26:27], v[130:131], v[26:27], v[190:191] op_sel_hi:[0,1,1]
	v_mul_f32_e32 v190, v70, v26
	v_fmac_f32_e32 v190, v27, v71
	v_pk_fma_f32 v[28:29], v[130:131], v[28:29], v[192:193] op_sel_hi:[0,1,1]
	s_waitcnt lgkmcnt(15)
	v_mul_f32_e32 v45, v82, v26
	v_fmac_f32_e32 v190, v28, v72
	v_fmac_f32_e32 v45, v27, v83
	v_pk_mul_f32 v[66:67], v[66:67], v[46:47] op_sel_hi:[1,0]
	v_pk_mul_f32 v[46:47], v[68:69], v[46:47] op_sel_hi:[1,0]
	v_fmac_f32_e32 v190, v29, v73
	v_pk_fma_f32 v[46:47], v[28:29], v[76:77], v[46:47]
	v_fmac_f32_e32 v45, v28, v84
	v_add_f32_dpp v28, v190, v190 row_ror:8 row_mask:0xf bank_mask:0xf bound_ctrl:1
	v_pk_fma_f32 v[26:27], v[26:27], v[74:75], v[66:67]
	v_fmac_f32_e32 v45, v29, v85
	v_add_f32_dpp v28, v28, v28 row_ror:4 row_mask:0xf bank_mask:0xf bound_ctrl:1
	s_waitcnt lgkmcnt(14)
	v_pk_mul_f32 v[66:67], v[114:115], v[194:195] op_sel_hi:[1,0]
	v_pk_mul_f32 v[68:69], v[116:117], v[194:195] op_sel_hi:[1,0]
	v_add_f32_dpp v28, v28, v28 row_ror:2 row_mask:0xf bank_mask:0xf bound_ctrl:1
	v_mov_b32_e32 v70, v195
	s_waitcnt lgkmcnt(13)
	v_pk_mul_f32 v[74:75], v[118:119], v[70:71] op_sel_hi:[1,0]
	v_add_f32_dpp v28, v28, v28 row_ror:1 row_mask:0xf bank_mask:0xf bound_ctrl:1
	v_pk_fma_f32 v[26:27], v[28:29], v[78:79], v[26:27] op_sel_hi:[0,1,1]
	v_pk_fma_f32 v[28:29], v[28:29], v[80:81], v[46:47] op_sel_hi:[0,1,1]
	v_mul_f32_e32 v46, v98, v26
	v_fmac_f32_e32 v46, v27, v99
	v_fmac_f32_e32 v46, v28, v100
	v_fmac_f32_e32 v46, v29, v101
	v_mul_f32_e32 v47, v86, v26
	v_fmac_f32_e32 v47, v27, v87
	v_add_f32_dpp v46, v46, v46 row_ror:8 row_mask:0xf bank_mask:0xf bound_ctrl:1
	v_fmac_f32_e32 v47, v28, v88
	v_fmac_f32_e32 v47, v29, v89
	v_add_f32_dpp v46, v46, v46 row_ror:4 row_mask:0xf bank_mask:0xf bound_ctrl:1
	v_pk_fma_f32 v[26:27], v[26:27], v[90:91], v[66:67]
	v_pk_fma_f32 v[28:29], v[28:29], v[92:93], v[68:69]
	v_add_f32_dpp v46, v46, v46 row_ror:2 row_mask:0xf bank_mask:0xf bound_ctrl:1
	v_pk_mul_f32 v[70:71], v[120:121], v[70:71] op_sel_hi:[1,0]
	s_waitcnt lgkmcnt(3)
; template <int CTRL> DI float dpp_get(float x) { return __int_as_float(__builtin_amdgcn_update_dpp(0, __float_as_int(x), CTRL, 0xf, 0xf, false)); }
; DI void scan_chunk(const float* buf, f32x4& S, int w, int rw, int kg, float& ys) {
;     ...
;   const bool b3 = (kg & 8) != 0, b2 = (kg & 4) != 0, b1 = (kg & 2) != 0, b0 = (kg & 1) != 0;
;   float t[8], u[4], v2[2];
; #pragma unroll
;   for (int j = 0; j < 8; ++j) { float keep = b3 ? yp[j + 8] : yp[j], send = b3 ? yp[j] : yp[j + 8]; t[j] = keep + dpp_get<0x140>(send); }
; #pragma unroll
;   for (int j = 0; j < 4; ++j) { float keep = b2 ? t[j + 4] : t[j], send = b2 ? t[j] : t[j + 4]; u[j] = keep + dpp_get<0x141>(send); }
; #pragma unroll
;   for (int j = 0; j < 2; ++j) { float keep = b1 ? u[j + 2] : u[j], send = b1 ? u[j] : u[j + 2]; v2[j] = keep + dpp_get<0x4E>(send); }
;   { float keep = b0 ? v2[1] : v2[0], send = b0 ? v2[0] : v2[1]; ys = keep + dpp_get<0xB1>(send); }
; }
; DI void scan_job(const int tid_, const Params& p, int l, int job, char* s0, char* s1, char* s2) {
;     ...
;       Y[(size_t)(tok0 + (c + 1) * 16 + kg) * 512 + h * 64 + row] = ys;
;       if (c + 2 < nchunks) scan_lstore(tid_, B, buf0);
	v_pk_mul_f32 v[82:83], v[162:163], v[196:197] op_sel_hi:[1,0]
	v_add_f32_dpp v46, v46, v46 row_ror:1 row_mask:0xf bank_mask:0xf bound_ctrl:1
	v_pk_fma_f32 v[26:27], v[46:47], v[106:107], v[26:27] op_sel_hi:[0,1,1]
	v_pk_fma_f32 v[28:29], v[46:47], v[108:109], v[28:29] op_sel_hi:[0,1,1]
	v_mul_f32_e32 v46, v102, v26
	v_fmac_f32_e32 v46, v27, v103
	v_fmac_f32_e32 v46, v28, v104
	v_fmac_f32_e32 v46, v29, v105
	v_mul_f32_e32 v68, v122, v26
	v_fmac_f32_e32 v68, v27, v123
	v_add_f32_dpp v46, v46, v46 row_ror:8 row_mask:0xf bank_mask:0xf bound_ctrl:1
	v_fmac_f32_e32 v68, v28, v124
	v_pk_fma_f32 v[26:27], v[26:27], v[94:95], v[74:75]
	v_add_f32_dpp v46, v46, v46 row_ror:4 row_mask:0xf bank_mask:0xf bound_ctrl:1
	v_fmac_f32_e32 v68, v29, v125
	v_pk_fma_f32 v[28:29], v[28:29], v[96:97], v[70:71]
	v_add_f32_dpp v46, v46, v46 row_ror:2 row_mask:0xf bank_mask:0xf bound_ctrl:1
	v_pk_mul_f32 v[76:77], v[164:165], v[196:197] op_sel_hi:[1,0]
	v_mov_b32_e32 v114, v197
	v_add_f32_dpp v46, v46, v46 row_ror:1 row_mask:0xf bank_mask:0xf bound_ctrl:1
	v_pk_fma_f32 v[26:27], v[46:47], v[110:111], v[26:27] op_sel_hi:[0,1,1]
	v_pk_fma_f32 v[28:29], v[46:47], v[112:113], v[28:29] op_sel_hi:[0,1,1]
	v_mul_f32_e32 v46, v146, v26
	v_fmac_f32_e32 v46, v27, v147
	v_fmac_f32_e32 v46, v28, v148
	v_fmac_f32_e32 v46, v29, v149
	v_mul_f32_e32 v69, v126, v26
	v_fmac_f32_e32 v69, v27, v127
	v_add_f32_dpp v46, v46, v46 row_ror:8 row_mask:0xf bank_mask:0xf bound_ctrl:1
	v_fmac_f32_e32 v69, v28, v128
	v_pk_fma_f32 v[26:27], v[26:27], v[138:139], v[82:83]
	v_add_f32_dpp v46, v46, v46 row_ror:4 row_mask:0xf bank_mask:0xf bound_ctrl:1
	v_fmac_f32_e32 v69, v29, v129
	v_pk_fma_f32 v[28:29], v[28:29], v[140:141], v[76:77]
	v_add_f32_dpp v46, v46, v46 row_ror:2 row_mask:0xf bank_mask:0xf bound_ctrl:1
	s_waitcnt lgkmcnt(2)
	v_pk_mul_f32 v[118:119], v[172:173], v[114:115] op_sel_hi:[1,0]
	v_pk_mul_f32 v[66:67], v[174:175], v[114:115] op_sel_hi:[1,0]
	v_add_f32_dpp v46, v46, v46 row_ror:1 row_mask:0xf bank_mask:0xf bound_ctrl:1
	v_pk_fma_f32 v[26:27], v[46:47], v[154:155], v[26:27] op_sel_hi:[0,1,1]
	v_pk_fma_f32 v[28:29], v[46:47], v[156:157], v[28:29] op_sel_hi:[0,1,1]
	v_mul_f32_e32 v46, v150, v26
	v_fmac_f32_e32 v46, v27, v151
	v_fmac_f32_e32 v46, v28, v152
	v_fmac_f32_e32 v46, v29, v153
	s_waitcnt lgkmcnt(1)
	v_mul_f32_e32 v70, v182, v26
	v_fmac_f32_e32 v70, v27, v183
	v_add_f32_dpp v46, v46, v46 row_ror:8 row_mask:0xf bank_mask:0xf bound_ctrl:1
	v_fmac_f32_e32 v70, v28, v184
	v_fmac_f32_e32 v70, v29, v185
	v_add_f32_dpp v46, v46, v46 row_ror:4 row_mask:0xf bank_mask:0xf bound_ctrl:1
	v_pk_fma_f32 v[26:27], v[26:27], v[142:143], v[118:119]
	v_pk_fma_f32 v[28:29], v[28:29], v[144:145], v[66:67]
	v_add_f32_dpp v46, v46, v46 row_ror:2 row_mask:0xf bank_mask:0xf bound_ctrl:1
	v_cndmask_b32_e64 v66, v198, v0, s[40:41]
	v_cndmask_b32_e64 v0, v0, v198, s[40:41]
	v_add_f32_dpp v46, v46, v46 row_ror:1 row_mask:0xf bank_mask:0xf bound_ctrl:1
	v_pk_fma_f32 v[26:27], v[46:47], v[158:159], v[26:27] op_sel_hi:[0,1,1]
	v_add_f32_dpp v0, v0, v66 row_mirror row_mask:0xf bank_mask:0xf bound_ctrl:1
	v_cndmask_b32_e64 v66, v199, v62, s[40:41]
	v_cndmask_b32_e64 v62, v62, v199, s[40:41]
	v_pk_fma_f32 v[28:29], v[46:47], v[160:161], v[28:29] op_sel_hi:[0,1,1]
	s_waitcnt lgkmcnt(0)
	v_mul_f32_e32 v46, v186, v26
	v_add_f32_dpp v62, v62, v66 row_mirror row_mask:0xf bank_mask:0xf bound_ctrl:1
	v_cndmask_b32_e64 v66, v45, v63, s[40:41]
	v_cndmask_b32_e64 v45, v63, v45, s[40:41]
	v_cndmask_b32_e64 v63, v47, v64, s[40:41]
	v_cndmask_b32_e64 v47, v64, v47, s[40:41]
	v_fmac_f32_e32 v46, v27, v187
	v_cndmask_b32_e64 v64, v65, v68, s[40:41]
	v_add_f32_dpp v47, v47, v63 row_mirror row_mask:0xf bank_mask:0xf bound_ctrl:1
	v_cndmask_b32_e64 v63, v68, v65, s[40:41]
	v_fmac_f32_e32 v46, v28, v188
	v_cndmask_b32_e64 v65, v131, v69, s[40:41]
	v_add_f32_dpp v63, v64, v63 row_mirror row_mask:0xf bank_mask:0xf bound_ctrl:1
	v_cndmask_b32_e64 v64, v69, v131, s[40:41]
	v_fmac_f32_e32 v46, v29, v189
	v_add_f32_dpp v45, v45, v66 row_mirror row_mask:0xf bank_mask:0xf bound_ctrl:1
	v_add_f32_dpp v64, v65, v64 row_mirror row_mask:0xf bank_mask:0xf bound_ctrl:1
	v_cndmask_b32_e64 v65, v70, v135, s[40:41]
	v_cndmask_b32_e64 v66, v135, v70, s[40:41]
	s_nop 1
	v_add_f32_dpp v65, v66, v65 row_mirror row_mask:0xf bank_mask:0xf bound_ctrl:1
	v_cndmask_b32_e64 v66, v46, v181, s[40:41]
	v_cndmask_b32_e64 v46, v181, v46, s[40:41]
	s_nop 1
	v_add_f32_dpp v46, v46, v66 row_mirror row_mask:0xf bank_mask:0xf bound_ctrl:1
	v_cndmask_b32_e64 v66, v63, v0, s[42:43]
	v_cndmask_b32_e64 v0, v0, v63, s[42:43]
	v_cndmask_b32_e64 v63, v64, v62, s[42:43]
	v_cndmask_b32_e64 v62, v62, v64, s[42:43]
	v_add_f32_dpp v0, v0, v66 row_half_mirror row_mask:0xf bank_mask:0xf bound_ctrl:1
	s_nop 0
	v_add_f32_dpp v62, v62, v63 row_half_mirror row_mask:0xf bank_mask:0xf bound_ctrl:1
	v_cndmask_b32_e64 v63, v65, v45, s[42:43]
	v_cndmask_b32_e64 v45, v45, v65, s[42:43]
	s_nop 1
	v_add_f32_dpp v45, v45, v63 row_half_mirror row_mask:0xf bank_mask:0xf bound_ctrl:1
	v_cndmask_b32_e64 v63, v46, v47, s[42:43]
	v_cndmask_b32_e64 v46, v47, v46, s[42:43]
	v_cndmask_b32_e64 v47, v45, v0, s[44:45]
	v_cndmask_b32_e64 v0, v0, v45, s[44:45]
	v_add_f32_dpp v46, v46, v63 row_half_mirror row_mask:0xf bank_mask:0xf bound_ctrl:1
	v_cndmask_b32_e64 v45, v46, v62, s[44:45]
	v_cndmask_b32_e64 v46, v62, v46, s[44:45]
	v_add_f32_dpp v0, v0, v47 quad_perm:[2,3,0,1] row_mask:0xf bank_mask:0xf bound_ctrl:1
	s_nop 0
	v_add_f32_dpp v45, v46, v45 quad_perm:[2,3,0,1] row_mask:0xf bank_mask:0xf bound_ctrl:1
	v_cndmask_b32_e64 v46, v45, v0, s[46:47]
	v_cndmask_b32_e64 v0, v0, v45, s[46:47]
	s_nop 1
	v_add_f32_dpp v46, v0, v46 quad_perm:[1,0,3,2] row_mask:0xf bank_mask:0xf bound_ctrl:1
	v_add_u32_e32 v0, 16, v44
	v_lshlrev_b64 v[44:45], 11, v[0:1]
	v_lshl_add_u64 v[44:45], v[36:37], 0, v[44:45]
	s_waitcnt lgkmcnt(0)
	flat_store_dword v[44:45], v46
	s_cbranch_vccnz .LBB0_182
	s_waitcnt vmcnt(1)
	v_lshlrev_b32_e32 v0, 16, v61
	v_lshlrev_b32_e32 v44, 16, v18
	v_and_b32_e32 v45, 0xffff0000, v18
	v_lshlrev_b32_e32 v46, 16, v19
	v_and_b32_e32 v47, 0xffff0000, v19
	ds_write_b128 v52, v[14:17]
	ds_write_b32 v53, v0 offset:20480
	ds_write_b128 v54, v[44:47] offset:4096
	v_lshlrev_b32_e32 v44, 16, v20
	v_and_b32_e32 v45, 0xffff0000, v20
	v_lshlrev_b32_e32 v46, 16, v21
	v_and_b32_e32 v47, 0xffff0000, v21
	ds_write_b128 v54, v[44:47] offset:4112
	v_lshlrev_b32_e32 v44, 16, v22
	v_and_b32_e32 v45, 0xffff0000, v22
	v_lshlrev_b32_e32 v46, 16, v23
	v_and_b32_e32 v47, 0xffff0000, v23
	ds_write_b128 v54, v[44:47] offset:12288
	v_lshlrev_b32_e32 v44, 16, v24
	v_and_b32_e32 v45, 0xffff0000, v24
	v_lshlrev_b32_e32 v46, 16, v25
	v_and_b32_e32 v47, 0xffff0000, v25
	ds_write_b128 v54, v[44:47] offset:12304
	s_branch .LBB0_182
